# lin_l3: batch V/C tile loads (8 loads, counted vmcnt); epilogue row-sum butterflies via DPP adds + permlane16 swap instead of ds_bpermute (bit-identical)
# speedup vs baseline: 1.0069x; 1.0047x over previous
; #define LAS __attribute__((address_space(3)))
; DI unsigned pk2(float lo, float hi) { f32x2 v = {lo, hi}; bf16x2_t b = __builtin_convertvector(v, bf16x2_t); return __builtin_bit_cast(unsigned, b); }
; DI float shup(float v, int o, int lane) { return __int_as_float(__builtin_amdgcn_ds_bpermute((lane - o) << 2, __float_as_int(v))); }
; DI void prep_scalars_b(LAS float* F, int wave, int lane) {
;     __syncthreads();
;     if (wave == 0) {
;         const float a0 = F[F_LF + 2 * lane], a1 = F[F_LF + 2 * lane + 1]; float s = a0 + a1;
; #pragma unroll
;         for (int o = 1; o < 64; o <<= 1) { const float t = shup(s, o, lane); if (lane >= o) s += t; }
;         const float bh1 = s, bh0 = s - a1;
;         const float A0 = F[F_LI + 2 * lane] - bh0, A1 = F[F_LI + 2 * lane + 1] - bh1;
;         float mx2 = fmaxf(A0, A1);
; #pragma unroll
;         for (int o = 1; o < 64; o <<= 1) { const float t = shup(mx2, o, lane); if (lane >= o) mx2 = fmaxf(mx2, t); }
;         float prev = shup(mx2, 1, lane); if (lane == 0) prev = -INFINITY;
;         F[F_BH + 2 * lane] = bh0; F[F_BH + 2 * lane + 1] = bh1; F[F_A + 2 * lane] = A0; F[F_A + 2 * lane + 1] = A1;
;         F[F_CM + 2 * lane] = fmaxf(prev, A0); F[F_CM + 2 * lane + 1] = mx2;
;     }
; DI void lin_l3(CArgs& a, LAS unsigned char* lds, int l, int item, int tid_, int wave, int lane_) {
;     ...
;     { const bf16_t* vt = (const bf16_t*)(a.ws + B_VT) + (size_t)(mx * 512 + h * 128) * T_ + t0;
; #pragma unroll
;         for (int i = 0; i < 4; ++i) { const int cv = tid + 512 * i, v = cv >> 4, cc = cv & 15; *(LAS u32x4*)(Vs + v * 136 + 8 * cc) = *(const u32x4*)(vt + (size_t)v * T_ + 8 * cc); } }
;     { const float* ck = (const float*)(a.ws + WS_LKV) + (size_t)item * 8192;
; #pragma unroll
;         for (int i = 0; i < 2; ++i) { const int cv = tid + 512 * i, v = cv >> 3, cc = cv & 7; const f32x4 f0 = *(const f32x4*)(ck + v * 64 + 8 * cc), f1 = *(const f32x4*)(ck + v * 64 + 8 * cc + 4);
;             u32x4 w; w.x = pk2(f0[0], f0[1]); w.y = pk2(f0[2], f0[3]); w.z = pk2(f1[0], f1[1]); w.w = pk2(f1[2], f1[3]); *(LAS u32x4*)(Cs + v * 72 + 8 * cc) = w; } }
.LBB0_241:
	s_ashr_i32 s0, s2, 1
	s_and_b32 s0, s0, 0xfffffe00
	s_lshl_b32 s3, s14, 7
	s_or_b32 s0, s3, s0
	s_ashr_i32 s1, s0, 31
	s_lshl_b64 s[0:1], s[0:1], 16
	s_add_u32 s0, s28, s0
	s_addc_u32 s1, s29, s1
	s_lshl_b32 s4, s36, 1
	s_add_u32 s0, s0, s4
	v_lshlrev_b32_e32 v0, 1, v0
	v_ashrrev_i32_e32 v8, 4, v114
	s_addc_u32 s1, s1, 0
	v_and_b32_e32 v80, 0xf0, v0
	v_ashrrev_i32_e32 v9, 31, v8
	v_lshl_add_u64 v[6:7], s[0:1], 0, v[80:81]
	v_lshlrev_b64 v[2:3], 16, v[8:9]
	v_lshl_add_u64 v[2:3], v[6:7], 0, v[2:3]
	global_load_dwordx4 v[188:191], v[2:3], off
	v_add_u32_e32 v0, 0, v80
	v_mad_u64_u32 v[216:217], s[0:1], v8, s35, v[0:1]
	v_add_u32_e32 v12, 0x200, v114
	v_ashrrev_i32_e32 v8, 4, v12
	v_ashrrev_i32_e32 v9, 31, v8
	v_lshlrev_b64 v[2:3], 16, v[8:9]
	v_lshl_add_u64 v[2:3], v[6:7], 0, v[2:3]
	global_load_dwordx4 v[192:195], v[2:3], off
	v_mad_u64_u32 v[218:219], s[0:1], v8, s35, v[0:1]
	v_add_u32_e32 v2, 0x400, v114
	v_ashrrev_i32_e32 v8, 4, v2
	v_ashrrev_i32_e32 v9, 31, v8
	v_lshlrev_b64 v[2:3], 16, v[8:9]
	v_lshl_add_u64 v[2:3], v[6:7], 0, v[2:3]
	global_load_dwordx4 v[196:199], v[2:3], off
	v_mad_u64_u32 v[224:225], s[0:1], v8, s35, v[0:1]
	v_add_u32_e32 v2, 0x600, v114
	v_ashrrev_i32_e32 v8, 4, v2
	v_ashrrev_i32_e32 v9, 31, v8
	v_lshlrev_b64 v[2:3], 16, v[8:9]
	v_lshl_add_u64 v[2:3], v[6:7], 0, v[2:3]
	global_load_dwordx4 v[200:203], v[2:3], off
	v_mad_u64_u32 v[6:7], s[0:1], v8, s35, v[0:1]
	v_mov_b32_e32 v43, v81
	v_lshlrev_b64 v[10:11], 2, v[42:43]
	s_add_i32 s5, 0, 0x11800
	v_and_b32_e32 v117, 63, v114
	s_andn2_b64 vcc, exec, s[94:95]
	v_lshlrev_b32_e32 v121, 2, v117
	v_cmp_gt_u32_e64 s[12:13], 32, v117
	v_lshlrev_b32_e32 v0, 6, v1
	v_ashrrev_i32_e32 v1, 31, v0
	v_lshl_add_u64 v[0:1], v[0:1], 2, v[10:11]
	v_lshl_add_u32 v8, v42, 1, s5
	v_ashrrev_i32_e32 v9, 3, v12
	v_lshl_add_u64 v[4:5], s[64:65], 0, v[0:1]
	global_load_dwordx4 v[204:207], v[4:5], off
	global_load_dwordx4 v[208:211], v[4:5], off offset:-16
	v_lshlrev_b32_e32 v0, 6, v9
	v_ashrrev_i32_e32 v1, 31, v0
	v_lshl_add_u64 v[0:1], v[0:1], 2, v[10:11]
	v_lshl_add_u64 v[4:5], s[64:65], 0, v[0:1]
	global_load_dwordx4 v[212:215], v[4:5], off
	global_load_dwordx4 v[226:229], v[4:5], off offset:-16
	s_waitcnt vmcnt(7)
	ds_write_b128 v216, v[188:191] offset:36864
	s_waitcnt vmcnt(6)
	ds_write_b128 v218, v[192:195] offset:36864
	s_waitcnt vmcnt(5)
	ds_write_b128 v224, v[196:199] offset:36864
	s_waitcnt vmcnt(4)
	ds_write_b128 v6, v[200:203] offset:36864
	s_waitcnt vmcnt(2)
	v_cvt_pk_bf16_f32 v4, v208, v209
	v_cvt_pk_bf16_f32 v5, v210, v211
	v_cvt_pk_bf16_f32 v6, v204, v205
	v_cvt_pk_bf16_f32 v7, v206, v207
	v_add_u32_e32 v0, v8, v50
	ds_write_b128 v0, v[4:7]
	s_waitcnt vmcnt(0)
	v_cvt_pk_bf16_f32 v4, v226, v227
	v_cvt_pk_bf16_f32 v5, v228, v229
	v_cvt_pk_bf16_f32 v6, v212, v213
	v_cvt_pk_bf16_f32 v7, v214, v215
	v_mad_u64_u32 v[0:1], s[0:1], v9, s34, v[8:9]
	ds_write_b128 v0, v[4:7]
	s_waitcnt lgkmcnt(0)
	s_barrier
	s_cbranch_vccnz .LBB0_243
	v_lshl_add_u32 v0, v117, 3, 0
	v_add_u32_e32 v6, 0x16000, v0
	ds_read2st64_b64 v[0:3], v6 offset1:1
	v_add_u32_e32 v7, -4, v121
	v_cmp_eq_u32_e32 vcc, 0, v117
	v_add_u32_e32 v8, -8, v121
	v_cmp_gt_u32_e64 s[14:15], 2, v117
	s_waitcnt lgkmcnt(0)
	v_add_f32_e32 v0, v0, v1
	ds_bpermute_b32 v4, v7, v0
	v_add_u32_e32 v9, -16, v121
	v_cmp_gt_u32_e64 s[16:17], 4, v117
	v_subrev_u32_e32 v10, 32, v121
	v_cmp_gt_u32_e64 s[18:19], 8, v117
	s_waitcnt lgkmcnt(0)
	v_add_f32_e32 v4, v0, v4
	v_cndmask_b32_e32 v0, v4, v0, vcc
	ds_bpermute_b32 v4, v8, v0
	v_subrev_u32_e32 v11, 64, v121
	v_cmp_gt_u32_e64 s[20:21], 16, v117
	v_add_u32_e32 v12, 0xffffff80, v121
	s_waitcnt lgkmcnt(0)
	v_add_f32_e32 v4, v0, v4
	v_cndmask_b32_e64 v0, v4, v0, s[14:15]
	ds_bpermute_b32 v4, v9, v0
	s_waitcnt lgkmcnt(0)
	v_add_f32_e32 v4, v0, v4
	v_cndmask_b32_e64 v0, v4, v0, s[16:17]
	ds_bpermute_b32 v4, v10, v0
	s_waitcnt lgkmcnt(0)
	v_add_f32_e32 v4, v0, v4
	v_cndmask_b32_e64 v0, v4, v0, s[18:19]
	ds_bpermute_b32 v4, v11, v0
	s_waitcnt lgkmcnt(0)
	v_add_f32_e32 v4, v0, v4
	v_cndmask_b32_e64 v0, v4, v0, s[20:21]
	ds_bpermute_b32 v4, v12, v0
	s_waitcnt lgkmcnt(0)
	v_add_f32_e32 v4, v0, v4
	v_cndmask_b32_e64 v5, v4, v0, s[12:13]
	v_sub_f32_e32 v4, v5, v1
	v_pk_add_f32 v[0:1], v[2:3], v[4:5] neg_lo:[0,1] neg_hi:[0,1]
	ds_write2st64_b64 v6, v[4:5], v[0:1] offset0:2 offset1:3
	v_max_f32_e32 v2, v0, v1
	ds_bpermute_b32 v3, v7, v2
	s_waitcnt lgkmcnt(0)
	v_max_f32_e32 v3, v3, v3
	v_max_f32_e32 v3, v2, v3
	v_cndmask_b32_e32 v2, v3, v2, vcc
	ds_bpermute_b32 v3, v8, v2
	s_waitcnt lgkmcnt(0)
	v_max_f32_e32 v3, v3, v3
	v_max_f32_e32 v3, v2, v3
	v_cndmask_b32_e64 v2, v3, v2, s[14:15]
	ds_bpermute_b32 v3, v9, v2
	s_waitcnt lgkmcnt(0)
	v_max_f32_e32 v3, v3, v3
	v_max_f32_e32 v3, v2, v3
	v_cndmask_b32_e64 v2, v3, v2, s[16:17]
	ds_bpermute_b32 v3, v10, v2
	s_waitcnt lgkmcnt(0)
	v_max_f32_e32 v3, v3, v3
	v_max_f32_e32 v3, v2, v3
	v_cndmask_b32_e64 v2, v3, v2, s[18:19]
	ds_bpermute_b32 v3, v11, v2
	s_waitcnt lgkmcnt(0)
	v_max_f32_e32 v3, v3, v3
	v_max_f32_e32 v3, v2, v3
	v_cndmask_b32_e64 v2, v3, v2, s[20:21]
	ds_bpermute_b32 v3, v12, v2
	v_max_f32_e32 v8, v2, v2
	s_waitcnt lgkmcnt(0)
	v_max_f32_e32 v3, v3, v3
	v_max_f32_e32 v3, v8, v3
	v_cndmask_b32_e64 v3, v3, v2, s[12:13]
	ds_bpermute_b32 v2, v7, v3
	s_waitcnt lgkmcnt(0)
	v_cndmask_b32_e32 v2, v2, v223, vcc
	v_max_f32_e32 v1, v2, v2
	v_max_f32_e32 v2, v1, v0
	ds_write_b64 v6, v[2:3] offset:2048

; DI float shx(float v, int o, int lane) { return __int_as_float(__builtin_amdgcn_ds_bpermute((lane ^ o) << 2, __float_as_int(v))); }
; DI int crow(int i, int hh) { return (i & 3) + 8 * (i >> 2) + 4 * hh; }
; DI void lin_l3(CArgs& a, LAS unsigned char* lds, int l, int item, int tid_, int wave, int lane_) {
;     ...
;     for (int i = 0; i < 16; ++i) { const int tr = 32 * tb + crow(i, hh); const float inv = F[F_INV + tr]; float sc = F[F_SC + tr];
;         o[0][i] = (o[0][i] + sc * qc[0][i]) * inv; o[1][i] = (o[1][i] + sc * qc[1][i]) * inv;
;         float s = o[0][i] * o[0][i] + o[1][i] * o[1][i];
;         s += shx(s, 1, lane); s += shx(s, 2, lane); s += shx(s, 4, lane); s += shx(s, 8, lane); s += shx(s, 16, lane);
;         if (r == 0) F[F_SSQ + vh * 128 + tr] = s; }
.LBB0_258:
	v_cmp_gt_u32_e32 vcc, 32, v117
	s_and_b64 s[10:11], s[62:63], vcc
	s_and_saveexec_b64 s[0:1], s[10:11]
	ds_write_b32 v123, v80 offset:4096
	s_or_b64 exec, exec, s[0:1]
	v_lshl_add_u32 v140, v135, 2, s4
	s_waitcnt lgkmcnt(0)
	s_barrier
	ds_read2st64_b32 v[64:65], v140 offset0:12 offset1:16
	v_xor_b32_e32 v80, 4, v121
	v_xor_b32_e32 v141, 8, v121
	v_xor_b32_e32 v142, 16, v121
	v_xor_b32_e32 v143, 32, v121
	s_waitcnt lgkmcnt(0)
	v_fma_f32 v0, v32, v64, v0
	v_mul_f32_e32 v117, v65, v0
	v_fma_f32 v0, v48, v64, v16
	v_mul_f32_e32 v0, v65, v0
	v_mul_f32_e32 v16, v0, v0
	v_fmac_f32_e32 v16, v117, v117
	v_xor_b32_e32 v144, 64, v121
	v_cmp_eq_u32_e32 vcc, 0, v122
	v_lshl_add_u32 v121, v135, 2, s31
	s_nop 1
	v_add_f32_dpp v16, v16, v16 quad_perm:[1,0,3,2] row_mask:0xf bank_mask:0xf
	s_nop 1
	v_add_f32_dpp v16, v16, v16 quad_perm:[2,3,0,1] row_mask:0xf bank_mask:0xf
	s_nop 1
	v_add_f32_dpp v16, v16, v16 row_half_mirror row_mask:0xf bank_mask:0xf
	s_nop 1
	v_add_f32_dpp v16, v16, v16 row_mirror row_mask:0xf bank_mask:0xf
	v_mov_b32_e32 v32, v16
	s_nop 1
	v_permlane16_swap_b32_e32 v32, v16
	s_and_saveexec_b64 s[0:1], vcc
	s_cbranch_execz .LBB0_262
	s_waitcnt lgkmcnt(0)
	v_add_f32_e32 v16, v16, v32
	ds_write_b32 v121, v16 offset:5376
.LBB0_262:
	s_or_b64 exec, exec, s[0:1]
	v_or_b32_e32 v139, 1, v135
	v_lshl_add_u32 v16, v139, 2, s4
	ds_read2st64_b32 v[64:65], v16 offset0:12 offset1:16
	s_waitcnt lgkmcnt(0)
	v_fma_f32 v16, v49, v64, v17
	v_fma_f32 v1, v33, v64, v1
	v_mul_f32_e32 v136, v65, v16
	v_mul_f32_e32 v138, v65, v1
	v_mul_f32_e32 v1, v136, v136
	v_fmac_f32_e32 v1, v138, v138
	s_nop 1
	v_add_f32_dpp v1, v1, v1 quad_perm:[1,0,3,2] row_mask:0xf bank_mask:0xf
	s_nop 1
	v_add_f32_dpp v1, v1, v1 quad_perm:[2,3,0,1] row_mask:0xf bank_mask:0xf
	s_nop 1
	v_add_f32_dpp v1, v1, v1 row_half_mirror row_mask:0xf bank_mask:0xf
	s_nop 1
	v_add_f32_dpp v1, v1, v1 row_mirror row_mask:0xf bank_mask:0xf
	v_mov_b32_e32 v16, v1
	s_nop 1
	v_permlane16_swap_b32_e32 v16, v1
	s_and_saveexec_b64 s[0:1], vcc
	s_cbranch_execz .LBB0_264
	s_waitcnt lgkmcnt(0)
	v_add_f32_e32 v1, v1, v16
	ds_write_b32 v121, v1 offset:5380
.LBB0_264:
	s_or_b64 exec, exec, s[0:1]
	v_or_b32_e32 v137, 2, v135
	v_lshl_add_u32 v1, v137, 2, s4
	s_waitcnt lgkmcnt(0)
	ds_read2st64_b32 v[16:17], v1 offset0:12 offset1:16
	s_waitcnt lgkmcnt(0)
	v_fma_f32 v1, v34, v16, v2
	v_fma_f32 v2, v50, v16, v18
	v_mul_f32_e32 v132, v17, v2
	v_mul_f32_e32 v134, v17, v1
	v_mul_f32_e32 v1, v132, v132
	v_fmac_f32_e32 v1, v134, v134
	s_nop 1
	v_add_f32_dpp v1, v1, v1 quad_perm:[1,0,3,2] row_mask:0xf bank_mask:0xf
	s_nop 1
	v_add_f32_dpp v1, v1, v1 quad_perm:[2,3,0,1] row_mask:0xf bank_mask:0xf
	s_nop 1
	v_add_f32_dpp v1, v1, v1 row_half_mirror row_mask:0xf bank_mask:0xf
	s_nop 1
	v_add_f32_dpp v1, v1, v1 row_mirror row_mask:0xf bank_mask:0xf
	v_mov_b32_e32 v2, v1
	s_nop 1
	v_permlane16_swap_b32_e32 v2, v1
	s_and_saveexec_b64 s[0:1], vcc
	s_cbranch_execz .LBB0_266
	s_waitcnt lgkmcnt(0)
	v_add_f32_e32 v1, v1, v2
	ds_write_b32 v121, v1 offset:5384
.LBB0_266:
	s_or_b64 exec, exec, s[0:1]
	v_or_b32_e32 v130, 3, v135
	v_lshl_add_u32 v1, v130, 2, s4
	ds_read2st64_b32 v[16:17], v1 offset0:12 offset1:16
	s_waitcnt lgkmcnt(0)
	v_fma_f32 v2, v51, v16, v19
	v_fma_f32 v1, v35, v16, v3
	v_mul_f32_e32 v126, v17, v2
	v_mul_f32_e32 v128, v17, v1
	v_mul_f32_e32 v1, v126, v126
	v_fmac_f32_e32 v1, v128, v128
	s_nop 1
	v_add_f32_dpp v1, v1, v1 quad_perm:[1,0,3,2] row_mask:0xf bank_mask:0xf
	s_nop 1
	v_add_f32_dpp v1, v1, v1 quad_perm:[2,3,0,1] row_mask:0xf bank_mask:0xf
	s_nop 1
	v_add_f32_dpp v1, v1, v1 row_half_mirror row_mask:0xf bank_mask:0xf
	s_nop 1
	v_add_f32_dpp v1, v1, v1 row_mirror row_mask:0xf bank_mask:0xf
	v_mov_b32_e32 v2, v1
	s_nop 1
	v_permlane16_swap_b32_e32 v2, v1
	s_and_saveexec_b64 s[0:1], vcc
	s_cbranch_execz .LBB0_268
	s_waitcnt lgkmcnt(0)
	v_add_f32_e32 v1, v1, v2
	ds_write_b32 v121, v1 offset:5388
.LBB0_268:
	s_or_b64 exec, exec, s[0:1]
	v_or_b32_e32 v127, 8, v135
	v_lshl_add_u32 v122, v127, 2, s4
	s_waitcnt lgkmcnt(0)
	ds_read2st64_b32 v[2:3], v122 offset0:12 offset1:16
	s_waitcnt lgkmcnt(0)
	v_fma_f32 v1, v36, v2, v4
	v_fma_f32 v2, v52, v2, v20
	v_mul_f32_e32 v123, v3, v2
	v_mul_f32_e32 v125, v3, v1
	v_mul_f32_e32 v1, v123, v123
	v_fmac_f32_e32 v1, v125, v125
	s_nop 1
	v_add_f32_dpp v1, v1, v1 quad_perm:[1,0,3,2] row_mask:0xf bank_mask:0xf
	s_nop 1
	v_add_f32_dpp v1, v1, v1 quad_perm:[2,3,0,1] row_mask:0xf bank_mask:0xf
	s_nop 1
	v_add_f32_dpp v1, v1, v1 row_half_mirror row_mask:0xf bank_mask:0xf
	s_nop 1
	v_add_f32_dpp v1, v1, v1 row_mirror row_mask:0xf bank_mask:0xf
	v_mov_b32_e32 v2, v1
	s_nop 1
	v_permlane16_swap_b32_e32 v2, v1
	s_and_saveexec_b64 s[0:1], vcc
	s_cbranch_execz .LBB0_270
	s_waitcnt lgkmcnt(0)
	v_add_f32_e32 v1, v1, v2
	ds_write_b32 v121, v1 offset:5408
.LBB0_270:
	s_or_b64 exec, exec, s[0:1]
	v_or_b32_e32 v119, 9, v135
	v_lshl_add_u32 v1, v119, 2, s4
	s_waitcnt lgkmcnt(0)
	ds_read2st64_b32 v[2:3], v1 offset0:12 offset1:16
	s_waitcnt lgkmcnt(0)
	v_fma_f32 v1, v37, v2, v5
	v_fma_f32 v2, v53, v2, v21
	v_mul_f32_e32 v113, v3, v2
	v_mul_f32_e32 v118, v3, v1
	v_mul_f32_e32 v1, v113, v113
	v_fmac_f32_e32 v1, v118, v118
	s_nop 1
	v_add_f32_dpp v1, v1, v1 quad_perm:[1,0,3,2] row_mask:0xf bank_mask:0xf
	s_nop 1
	v_add_f32_dpp v1, v1, v1 quad_perm:[2,3,0,1] row_mask:0xf bank_mask:0xf
	s_nop 1
	v_add_f32_dpp v1, v1, v1 row_half_mirror row_mask:0xf bank_mask:0xf
	s_nop 1
	v_add_f32_dpp v1, v1, v1 row_mirror row_mask:0xf bank_mask:0xf
	v_mov_b32_e32 v2, v1
	s_nop 1
	v_permlane16_swap_b32_e32 v2, v1
	s_and_saveexec_b64 s[0:1], vcc
	s_cbranch_execz .LBB0_272
	s_waitcnt lgkmcnt(0)
	v_add_f32_e32 v1, v1, v2
	ds_write_b32 v121, v1 offset:5412
; DI float shx(float v, int o, int lane) { return __int_as_float(__builtin_amdgcn_ds_bpermute((lane ^ o) << 2, __float_as_int(v))); }
; DI int crow(int i, int hh) { return (i & 3) + 8 * (i >> 2) + 4 * hh; }
; DI void lin_l3(CArgs& a, LAS unsigned char* lds, int l, int item, int tid_, int wave, int lane_) {
;     ...
;     for (int i = 0; i < 16; ++i) { const int tr = 32 * tb + crow(i, hh); const float inv = F[F_INV + tr]; float sc = F[F_SC + tr];
;         o[0][i] = (o[0][i] + sc * qc[0][i]) * inv; o[1][i] = (o[1][i] + sc * qc[1][i]) * inv;
;         float s = o[0][i] * o[0][i] + o[1][i] * o[1][i];
;         s += shx(s, 1, lane); s += shx(s, 2, lane); s += shx(s, 4, lane); s += shx(s, 8, lane); s += shx(s, 16, lane);
;         if (r == 0) F[F_SSQ + vh * 128 + tr] = s; }
.LBB0_272:
	s_or_b64 exec, exec, s[0:1]
	v_or_b32_e32 v114, 10, v135
	v_lshl_add_u32 v1, v114, 2, s4
	s_waitcnt lgkmcnt(0)
	ds_read2st64_b32 v[2:3], v1 offset0:12 offset1:16
	s_waitcnt lgkmcnt(0)
	v_fma_f32 v1, v38, v2, v6
	v_fma_f32 v2, v54, v2, v22
	v_mul_f32_e32 v65, v3, v2
	v_mul_f32_e32 v112, v3, v1
	v_mul_f32_e32 v1, v65, v65
	v_fmac_f32_e32 v1, v112, v112
	s_nop 1
	v_add_f32_dpp v1, v1, v1 quad_perm:[1,0,3,2] row_mask:0xf bank_mask:0xf
	s_nop 1
	v_add_f32_dpp v1, v1, v1 quad_perm:[2,3,0,1] row_mask:0xf bank_mask:0xf
	s_nop 1
	v_add_f32_dpp v1, v1, v1 row_half_mirror row_mask:0xf bank_mask:0xf
	s_nop 1
	v_add_f32_dpp v1, v1, v1 row_mirror row_mask:0xf bank_mask:0xf
	v_mov_b32_e32 v2, v1
	s_nop 1
	v_permlane16_swap_b32_e32 v2, v1
	s_and_saveexec_b64 s[0:1], vcc
	s_cbranch_execz .LBB0_274
	s_waitcnt lgkmcnt(0)
	v_add_f32_e32 v1, v1, v2
	ds_write_b32 v121, v1 offset:5416
.LBB0_274:
	s_or_b64 exec, exec, s[0:1]
	v_or_b32_e32 v64, 11, v135
	v_lshl_add_u32 v1, v64, 2, s4
	s_waitcnt lgkmcnt(0)
	ds_read2st64_b32 v[2:3], v1 offset0:12 offset1:16
	s_waitcnt lgkmcnt(0)
	v_fma_f32 v1, v39, v2, v7
	v_fma_f32 v2, v55, v2, v23
	v_mul_f32_e32 v52, v3, v2
	v_mul_f32_e32 v54, v3, v1
	v_mul_f32_e32 v1, v52, v52
	v_fmac_f32_e32 v1, v54, v54
	s_nop 1
	v_add_f32_dpp v1, v1, v1 quad_perm:[1,0,3,2] row_mask:0xf bank_mask:0xf
	s_nop 1
	v_add_f32_dpp v1, v1, v1 quad_perm:[2,3,0,1] row_mask:0xf bank_mask:0xf
	s_nop 1
	v_add_f32_dpp v1, v1, v1 row_half_mirror row_mask:0xf bank_mask:0xf
	s_nop 1
	v_add_f32_dpp v1, v1, v1 row_mirror row_mask:0xf bank_mask:0xf
	v_mov_b32_e32 v2, v1
	s_nop 1
	v_permlane16_swap_b32_e32 v2, v1
	s_and_saveexec_b64 s[0:1], vcc
	s_cbranch_execz .LBB0_276
	s_waitcnt lgkmcnt(0)
	v_add_f32_e32 v1, v1, v2
	ds_write_b32 v121, v1 offset:5420
.LBB0_276:
	s_or_b64 exec, exec, s[0:1]
	v_or_b32_e32 v53, 16, v135
	v_lshl_add_u32 v49, v53, 2, s4
	s_waitcnt lgkmcnt(0)
	ds_read2st64_b32 v[2:3], v49 offset0:12 offset1:16
	s_waitcnt lgkmcnt(0)
	v_fma_f32 v1, v40, v2, v8
	v_fma_f32 v2, v56, v2, v24
	v_mul_f32_e32 v50, v3, v2
	v_mul_f32_e32 v51, v3, v1
	v_mul_f32_e32 v1, v50, v50
	v_fmac_f32_e32 v1, v51, v51
	s_nop 1
	v_add_f32_dpp v1, v1, v1 quad_perm:[1,0,3,2] row_mask:0xf bank_mask:0xf
	s_nop 1
	v_add_f32_dpp v1, v1, v1 quad_perm:[2,3,0,1] row_mask:0xf bank_mask:0xf
	s_nop 1
	v_add_f32_dpp v1, v1, v1 row_half_mirror row_mask:0xf bank_mask:0xf
	s_nop 1
	v_add_f32_dpp v1, v1, v1 row_mirror row_mask:0xf bank_mask:0xf
	v_mov_b32_e32 v2, v1
	s_nop 1
	v_permlane16_swap_b32_e32 v2, v1
	s_and_saveexec_b64 s[0:1], vcc
	s_cbranch_execz .LBB0_278
	s_waitcnt lgkmcnt(0)
	v_add_f32_e32 v1, v1, v2
	ds_write_b32 v121, v1 offset:5440
.LBB0_278:
	s_or_b64 exec, exec, s[0:1]
	v_or_b32_e32 v48, 17, v135
	v_lshl_add_u32 v1, v48, 2, s4
	s_waitcnt lgkmcnt(0)
	ds_read2st64_b32 v[2:3], v1 offset0:12 offset1:16
	s_waitcnt lgkmcnt(0)
	v_fma_f32 v1, v41, v2, v9
	v_fma_f32 v2, v57, v2, v25
	v_mul_f32_e32 v38, v3, v2
	v_mul_f32_e32 v40, v3, v1
	v_mul_f32_e32 v1, v38, v38
	v_fmac_f32_e32 v1, v40, v40
	s_nop 1
	v_add_f32_dpp v1, v1, v1 quad_perm:[1,0,3,2] row_mask:0xf bank_mask:0xf
	s_nop 1
	v_add_f32_dpp v1, v1, v1 quad_perm:[2,3,0,1] row_mask:0xf bank_mask:0xf
	s_nop 1
	v_add_f32_dpp v1, v1, v1 row_half_mirror row_mask:0xf bank_mask:0xf
	s_nop 1
	v_add_f32_dpp v1, v1, v1 row_mirror row_mask:0xf bank_mask:0xf
	v_mov_b32_e32 v2, v1
	s_nop 1
	v_permlane16_swap_b32_e32 v2, v1
	s_and_saveexec_b64 s[0:1], vcc
	s_cbranch_execz .LBB0_280
	s_waitcnt lgkmcnt(0)
	v_add_f32_e32 v1, v1, v2
	ds_write_b32 v121, v1 offset:5444
.LBB0_280:
	s_or_b64 exec, exec, s[0:1]
	v_or_b32_e32 v39, 18, v135
	v_lshl_add_u32 v1, v39, 2, s4
	s_waitcnt lgkmcnt(0)
	ds_read2st64_b32 v[2:3], v1 offset0:12 offset1:16
	s_waitcnt lgkmcnt(0)
	v_fma_f32 v1, v42, v2, v10
	v_fma_f32 v2, v58, v2, v26
	v_mul_f32_e32 v36, v3, v2
	v_mul_f32_e32 v37, v3, v1
	v_mul_f32_e32 v1, v36, v36
	v_fmac_f32_e32 v1, v37, v37
	s_nop 1
	v_add_f32_dpp v1, v1, v1 quad_perm:[1,0,3,2] row_mask:0xf bank_mask:0xf
	s_nop 1
	v_add_f32_dpp v1, v1, v1 quad_perm:[2,3,0,1] row_mask:0xf bank_mask:0xf
	s_nop 1
	v_add_f32_dpp v1, v1, v1 row_half_mirror row_mask:0xf bank_mask:0xf
	s_nop 1
	v_add_f32_dpp v1, v1, v1 row_mirror row_mask:0xf bank_mask:0xf
	v_mov_b32_e32 v2, v1
	s_nop 1
	v_permlane16_swap_b32_e32 v2, v1
	s_and_saveexec_b64 s[0:1], vcc
	s_cbranch_execz .LBB0_282
	s_waitcnt lgkmcnt(0)
	v_add_f32_e32 v1, v1, v2
	ds_write_b32 v121, v1 offset:5448
; DI float shx(float v, int o, int lane) { return __int_as_float(__builtin_amdgcn_ds_bpermute((lane ^ o) << 2, __float_as_int(v))); }
; DI int crow(int i, int hh) { return (i & 3) + 8 * (i >> 2) + 4 * hh; }
; DI void lin_l3(CArgs& a, LAS unsigned char* lds, int l, int item, int tid_, int wave, int lane_) {
;     ...
;     for (int i = 0; i < 16; ++i) { const int tr = 32 * tb + crow(i, hh); const float inv = F[F_INV + tr]; float sc = F[F_SC + tr];
;         o[0][i] = (o[0][i] + sc * qc[0][i]) * inv; o[1][i] = (o[1][i] + sc * qc[1][i]) * inv;
;         float s = o[0][i] * o[0][i] + o[1][i] * o[1][i];
;         s += shx(s, 1, lane); s += shx(s, 2, lane); s += shx(s, 4, lane); s += shx(s, 8, lane); s += shx(s, 16, lane);
;         if (r == 0) F[F_SSQ + vh * 128 + tr] = s; }
.LBB0_282:
	s_or_b64 exec, exec, s[0:1]
	v_or_b32_e32 v35, 19, v135
	v_lshl_add_u32 v1, v35, 2, s4
	s_waitcnt lgkmcnt(0)
	ds_read2st64_b32 v[2:3], v1 offset0:12 offset1:16
	s_waitcnt lgkmcnt(0)
	v_fma_f32 v1, v43, v2, v11
	v_fma_f32 v2, v59, v2, v27
	v_mul_f32_e32 v32, v3, v2
	v_mul_f32_e32 v34, v3, v1
	v_mul_f32_e32 v1, v32, v32
	v_fmac_f32_e32 v1, v34, v34
	s_nop 1
	v_add_f32_dpp v1, v1, v1 quad_perm:[1,0,3,2] row_mask:0xf bank_mask:0xf
	s_nop 1
	v_add_f32_dpp v1, v1, v1 quad_perm:[2,3,0,1] row_mask:0xf bank_mask:0xf
	s_nop 1
	v_add_f32_dpp v1, v1, v1 row_half_mirror row_mask:0xf bank_mask:0xf
	s_nop 1
	v_add_f32_dpp v1, v1, v1 row_mirror row_mask:0xf bank_mask:0xf
	v_mov_b32_e32 v2, v1
	s_nop 1
	v_permlane16_swap_b32_e32 v2, v1
	s_and_saveexec_b64 s[0:1], vcc
	s_cbranch_execz .LBB0_284
	s_waitcnt lgkmcnt(0)
	v_add_f32_e32 v1, v1, v2
	ds_write_b32 v121, v1 offset:5452
.LBB0_284:
	s_or_b64 exec, exec, s[0:1]
	v_or_b32_e32 v33, 24, v135
	v_lshl_add_u32 v25, v33, 2, s4
	s_waitcnt lgkmcnt(0)
	ds_read2st64_b32 v[2:3], v25 offset0:12 offset1:16
	s_waitcnt lgkmcnt(0)
	v_fma_f32 v1, v44, v2, v12
	v_fma_f32 v2, v60, v2, v28
	v_mul_f32_e32 v26, v3, v2
	v_mul_f32_e32 v27, v3, v1
	v_mul_f32_e32 v1, v26, v26
	v_fmac_f32_e32 v1, v27, v27
	s_nop 1
	v_add_f32_dpp v1, v1, v1 quad_perm:[1,0,3,2] row_mask:0xf bank_mask:0xf
	s_nop 1
	v_add_f32_dpp v1, v1, v1 quad_perm:[2,3,0,1] row_mask:0xf bank_mask:0xf
	s_nop 1
	v_add_f32_dpp v1, v1, v1 row_half_mirror row_mask:0xf bank_mask:0xf
	s_nop 1
	v_add_f32_dpp v1, v1, v1 row_mirror row_mask:0xf bank_mask:0xf
	v_mov_b32_e32 v2, v1
	s_nop 1
	v_permlane16_swap_b32_e32 v2, v1
	s_and_saveexec_b64 s[0:1], vcc
	s_cbranch_execz .LBB0_286
	s_waitcnt lgkmcnt(0)
	v_add_f32_e32 v1, v1, v2
	ds_write_b32 v121, v1 offset:5472
.LBB0_286:
	s_or_b64 exec, exec, s[0:1]
	v_or_b32_e32 v24, 25, v135
	v_lshl_add_u32 v1, v24, 2, s4
	s_waitcnt lgkmcnt(0)
	ds_read2st64_b32 v[2:3], v1 offset0:12 offset1:16
	s_waitcnt lgkmcnt(0)
	v_fma_f32 v1, v45, v2, v13
	v_fma_f32 v2, v61, v2, v29
	v_mul_f32_e32 v21, v3, v2
	v_mul_f32_e32 v23, v3, v1
	v_mul_f32_e32 v1, v21, v21
	v_fmac_f32_e32 v1, v23, v23
	s_nop 1
	v_add_f32_dpp v1, v1, v1 quad_perm:[1,0,3,2] row_mask:0xf bank_mask:0xf
	s_nop 1
	v_add_f32_dpp v1, v1, v1 quad_perm:[2,3,0,1] row_mask:0xf bank_mask:0xf
	s_nop 1
	v_add_f32_dpp v1, v1, v1 row_half_mirror row_mask:0xf bank_mask:0xf
	s_nop 1
	v_add_f32_dpp v1, v1, v1 row_mirror row_mask:0xf bank_mask:0xf
	v_mov_b32_e32 v2, v1
	s_nop 1
	v_permlane16_swap_b32_e32 v2, v1
	s_and_saveexec_b64 s[0:1], vcc
	s_cbranch_execz .LBB0_288
	s_waitcnt lgkmcnt(0)
	v_add_f32_e32 v1, v1, v2
	ds_write_b32 v121, v1 offset:5476
.LBB0_288:
	s_or_b64 exec, exec, s[0:1]
	v_or_b32_e32 v22, 26, v135
	v_lshl_add_u32 v1, v22, 2, s4
	s_waitcnt lgkmcnt(0)
	ds_read2st64_b32 v[2:3], v1 offset0:12 offset1:16
	s_waitcnt lgkmcnt(0)
	v_fma_f32 v1, v46, v2, v14
	v_fma_f32 v2, v62, v2, v30
	v_mul_f32_e32 v18, v3, v2
	v_mul_f32_e32 v20, v3, v1
	v_mul_f32_e32 v1, v18, v18
	v_fmac_f32_e32 v1, v20, v20
	s_nop 1
	v_add_f32_dpp v1, v1, v1 quad_perm:[1,0,3,2] row_mask:0xf bank_mask:0xf
	s_nop 1
	v_add_f32_dpp v1, v1, v1 quad_perm:[2,3,0,1] row_mask:0xf bank_mask:0xf
	s_nop 1
	v_add_f32_dpp v1, v1, v1 row_half_mirror row_mask:0xf bank_mask:0xf
	s_nop 1
	v_add_f32_dpp v1, v1, v1 row_mirror row_mask:0xf bank_mask:0xf
	v_mov_b32_e32 v2, v1
	s_nop 1
	v_permlane16_swap_b32_e32 v2, v1
	s_and_saveexec_b64 s[0:1], vcc
	s_cbranch_execz .LBB0_290
	s_waitcnt lgkmcnt(0)
	v_add_f32_e32 v1, v1, v2
	ds_write_b32 v121, v1 offset:5480
.LBB0_290:
	s_or_b64 exec, exec, s[0:1]
	v_or_b32_e32 v16, 27, v135
	v_lshl_add_u32 v1, v16, 2, s4
	s_waitcnt lgkmcnt(0)
	ds_read2st64_b32 v[2:3], v1 offset0:12 offset1:16
	s_waitcnt lgkmcnt(0)
	v_fmac_f32_e32 v31, v63, v2
	v_fmac_f32_e32 v15, v47, v2
	v_mul_f32_e32 v14, v3, v31
	v_mul_f32_e32 v15, v3, v15
	v_mul_f32_e32 v1, v14, v14
	v_fmac_f32_e32 v1, v15, v15
	s_nop 1
	v_add_f32_dpp v1, v1, v1 quad_perm:[1,0,3,2] row_mask:0xf bank_mask:0xf
	s_nop 1
	v_add_f32_dpp v1, v1, v1 quad_perm:[2,3,0,1] row_mask:0xf bank_mask:0xf
	s_nop 1
	v_add_f32_dpp v1, v1, v1 row_half_mirror row_mask:0xf bank_mask:0xf
	s_nop 1
	v_add_f32_dpp v1, v1, v1 row_mirror row_mask:0xf bank_mask:0xf
	v_mov_b32_e32 v2, v1
	s_nop 1
	v_permlane16_swap_b32_e32 v2, v1
	s_and_saveexec_b64 s[0:1], vcc
	s_cbranch_execz .LBB0_190
	s_waitcnt lgkmcnt(0)
	v_add_f32_e32 v1, v1, v2
	ds_write_b32 v121, v1 offset:5484
	s_branch .LBB0_190
